# t2_rows merge loop: partial vmcnt waits so row-1 compute overlaps row-2 loads (v17 + 4 lines)
# baseline (speedup 1.0000x reference)
; DI void t2_rows(unsigned char* ws, int gw, int NGW, int lane) {
;     ...
;     for (int t0 = gw; t0 < TCH; t0 += 2 * NGW) {
;         u32x4 raw[2][3]; float ls[2][3];
; #pragma unroll
;         for (int u = 0; u < 2; ++u) { const int t = t0 + u * NGW; if (t < TCH) {
; #pragma unroll
;                 for (int gq = 0; gq < 3; ++gq) { ls[u][gq] = LSE[((size_t)gq * TCH + t) * 4 + head]; raw[u][gq] = *(const u32x4*)(OG + ((size_t)gq * TCH + t) * 512 + lane * 8); } } }
.LBB0_998:
	s_ashr_i32 s9, s8, 31
	s_lshl_b64 s[6:7], s[8:9], 10
	v_lshl_add_u64 v[14:15], v[28:29], 0, s[6:7]
	s_add_u32 s6, s8, 0x4000
	s_addc_u32 s7, s9, 0
	v_lshl_add_u64 v[12:13], s[8:9], 4, v[26:27]
	v_lshl_add_u64 v[16:17], s[6:7], 4, v[26:27]
	s_lshl_b64 s[6:7], s[6:7], 10
	global_load_dword v35, v[12:13], off
	s_nop 0
	global_load_dwordx4 v[12:15], v[14:15], off
	s_nop 0
	global_load_dword v36, v[16:17], off
	v_lshl_add_u64 v[16:17], v[28:29], 0, s[6:7]
	s_add_u32 s6, s8, 0x8000
	s_addc_u32 s7, s9, 0
	v_lshl_add_u64 v[20:21], s[6:7], 4, v[26:27]
	s_lshl_b64 s[6:7], s[6:7], 10
	global_load_dwordx4 v[16:19], v[16:17], off
	s_nop 0
	global_load_dword v37, v[20:21], off
	v_lshl_add_u64 v[20:21], v[28:29], 0, s[6:7]
	global_load_dwordx4 v[20:23], v[20:21], off
	s_add_i32 s6, s8, s94
	s_cmpk_lt_i32 s6, 0x4000
	s_cselect_b64 s[10:11], -1, 0
	s_cmpk_gt_i32 s6, 0x3fff
	s_cbranch_scc1 .LBB0_1000
	s_ashr_i32 s7, s6, 31
	s_lshl_b64 s[12:13], s[6:7], 10
	v_lshl_add_u64 v[2:3], v[28:29], 0, s[12:13]
	s_add_u32 s12, s6, 0x4000
	s_addc_u32 s13, s7, 0
	v_lshl_add_u64 v[0:1], s[6:7], 4, v[26:27]
	v_lshl_add_u64 v[4:5], s[12:13], 4, v[26:27]
	s_lshl_b64 s[12:13], s[12:13], 10
	global_load_dword v32, v[0:1], off
	s_nop 0
	global_load_dwordx4 v[0:3], v[2:3], off
	s_nop 0
	global_load_dword v33, v[4:5], off
	v_lshl_add_u64 v[4:5], v[28:29], 0, s[12:13]
	s_add_u32 s12, s6, 0x8000
	s_addc_u32 s13, s7, 0
	v_lshl_add_u64 v[8:9], s[12:13], 4, v[26:27]
	s_lshl_b64 s[12:13], s[12:13], 10
	global_load_dwordx4 v[4:7], v[4:5], off
	s_nop 0
	global_load_dword v34, v[8:9], off
	v_lshl_add_u64 v[8:9], v[28:29], 0, s[12:13]
	global_load_dwordx4 v[8:11], v[8:9], off
	s_waitcnt vmcnt(6)
	s_branch .Lt2_go

; DI unsigned cvtpk(float lo, float hi) { f32x2_t v = {lo, hi}; bf16x2_t b = __builtin_convertvector(v, bf16x2_t); return __builtin_bit_cast(unsigned, b); }
; DI float fexp2(float x) { return __builtin_amdgcn_exp2f(x); }
; DI void unpack8(const u32x4& r, float (&v)[8]) { v[0] = bflo(r.x); v[1] = bfhi(r.x); v[2] = bflo(r.y); v[3] = bfhi(r.y); v[4] = bflo(r.z); v[5] = bfhi(r.z); v[6] = bflo(r.w); v[7] = bfhi(r.w); }
; DI void t2_rows(unsigned char* ws, int gw, int NGW, int lane) {
;     ...
; #pragma unroll
;         for (int u = 0; u < 2; ++u) { const int t = t0 + u * NGW; if (t < TCH) {
;                 const float M = fmaxf(ls[u][0], fmaxf(ls[u][1], ls[u][2])); float w0 = fexp2(ls[u][0] - M), w1 = fexp2(ls[u][1] - M), w2 = fexp2(ls[u][2] - M); const float rs = 1.f / (w0 + w1 + w2); w0 *= rs; w1 *= rs; w2 *= rs;
;                 float v0[8], v1[8], v2[8]; unpack8(raw[u][0], v0); unpack8(raw[u][1], v1); unpack8(raw[u][2], v2);
;                 float r[8];
; #pragma unroll
;                 for (int i = 0; i < 8; ++i) r[i] = w0 * v0[i] + w1 * v1[i] + w2 * v2[i];
;                 u32x4 o; o.x = cvtpk(r[0], r[1]); o.y = cvtpk(r[2], r[3]); o.z = cvtpk(r[4], r[5]); o.w = cvtpk(r[6], r[7]);
;                 *(u32x4*)(CB + (size_t)t * 1536 + lane * 8) = o; } }
.Lt2_go:
	v_max3_f32 v40, v35, v36, v37
	v_sub_f32_e32 v35, v35, v40
	v_exp_f32_e32 v39, v35
	v_sub_f32_e32 v35, v36, v40
	v_exp_f32_e32 v38, v35
	v_sub_f32_e32 v35, v37, v40
	v_exp_f32_e32 v35, v35
	v_lshlrev_b32_e32 v48, 16, v12
	v_add_f32_e32 v36, v39, v38
	v_and_b32_e32 v49, 0xffff0000, v16
	v_add_f32_e32 v36, v35, v36
	v_div_scale_f32 v37, s[12:13], v36, v36, 1.0
	v_rcp_f32_e32 v40, v37
	v_lshlrev_b32_e32 v46, 16, v16
	v_and_b32_e32 v47, 0xffff0000, v12
	v_lshlrev_b32_e32 v12, 16, v13
	v_fma_f32 v41, -v37, v40, 1.0
	v_fmac_f32_e32 v40, v41, v40
	v_div_scale_f32 v41, vcc, 1.0, v36, 1.0
	v_mul_f32_e32 v42, v41, v40
	v_fma_f32 v43, -v37, v42, v41
	v_fmac_f32_e32 v42, v43, v40
	v_fma_f32 v37, -v37, v42, v41
	v_div_fmas_f32 v37, v37, v40, v42
	v_div_fixup_f32 v36, v37, v36, 1.0
	v_mul_f32_e32 v40, v35, v36
	v_pk_mul_f32 v[36:37], v[38:39], v[36:37] op_sel_hi:[1,0]
	v_lshlrev_b32_e32 v16, 16, v21
	v_pk_mul_f32 v[48:49], v[36:37], v[48:49] op_sel:[1,0] op_sel_hi:[0,1]
	v_pk_fma_f32 v[46:47], v[36:37], v[46:47], v[48:49]
	v_and_b32_e32 v49, 0xffff0000, v13
	v_and_b32_e32 v13, 0xffff0000, v17
	v_lshlrev_b32_e32 v48, 16, v17
	v_pk_mul_f32 v[12:13], v[36:37], v[12:13] op_sel:[1,0] op_sel_hi:[0,1]
	v_and_b32_e32 v17, 0xffff0000, v21
	v_pk_fma_f32 v[12:13], v[36:37], v[48:49], v[12:13]
	v_and_b32_e32 v39, 0xffff0000, v15
	v_lshlrev_b32_e32 v42, 16, v15
	v_pk_fma_f32 v[16:17], v[40:41], v[16:17], v[12:13] op_sel_hi:[0,1,1]
	v_and_b32_e32 v13, 0xffff0000, v14
	v_lshlrev_b32_e32 v14, 16, v14
	v_and_b32_e32 v15, 0xffff0000, v18
	v_lshlrev_b32_e32 v12, 16, v18
	v_pk_mul_f32 v[14:15], v[36:37], v[14:15] op_sel:[1,0] op_sel_hi:[0,1]
	v_lshlrev_b32_e32 v38, 16, v19
	v_and_b32_e32 v43, 0xffff0000, v19
	v_lshlrev_b32_e32 v18, 16, v22
	v_and_b32_e32 v19, 0xffff0000, v22
	v_pk_fma_f32 v[12:13], v[36:37], v[12:13], v[14:15]
	v_lshlrev_b32_e32 v44, 16, v23
	v_pk_fma_f32 v[14:15], v[40:41], v[18:19], v[12:13] op_sel_hi:[0,1,1]
	v_pk_mul_f32 v[12:13], v[36:37], v[42:43] op_sel:[1,0] op_sel_hi:[0,1]
	v_and_b32_e32 v45, 0xffff0000, v23
	v_lshlrev_b32_e32 v50, 16, v20
	v_and_b32_e32 v51, 0xffff0000, v20
	v_pk_fma_f32 v[12:13], v[36:37], v[38:39], v[12:13]
	v_pk_fma_f32 v[46:47], v[40:41], v[50:51], v[46:47] op_sel_hi:[0,1,1]
	v_pk_fma_f32 v[18:19], v[40:41], v[44:45], v[12:13] op_sel_hi:[0,1,1]
	v_cvt_pk_bf16_f32 v12, v46, v47
	v_cvt_pk_bf16_f32 v13, v16, v17
	v_cvt_pk_bf16_f32 v14, v14, v15
	v_cvt_pk_bf16_f32 v15, v18, v19
	v_mad_i64_i32 v[16:17], s[8:9], s8, v213, v[30:31]
	s_andn2_b64 vcc, exec, s[10:11]
	global_store_dwordx4 v[16:17], v[12:15], off
	s_cbranch_vccnz .LBB0_997
	s_waitcnt vmcnt(1)
	s_nop 0
	v_max3_f32 v14, v32, v33, v34
	v_sub_f32_e32 v12, v32, v14
	v_exp_f32_e32 v13, v12
	v_sub_f32_e32 v12, v33, v14
	v_exp_f32_e32 v12, v12
	v_sub_f32_e32 v14, v34, v14
	v_exp_f32_e32 v15, v14
	v_lshlrev_b32_e32 v36, 16, v0
	v_add_f32_e32 v14, v13, v12
	v_and_b32_e32 v37, 0xffff0000, v4
	v_add_f32_e32 v14, v15, v14
	v_div_scale_f32 v16, s[8:9], v14, v14, 1.0
	v_rcp_f32_e32 v17, v16
	v_lshlrev_b32_e32 v22, 16, v4
	v_and_b32_e32 v23, 0xffff0000, v0
	v_lshlrev_b32_e32 v38, 16, v8
	v_fma_f32 v18, -v16, v17, 1.0
	v_fmac_f32_e32 v17, v18, v17
	v_div_scale_f32 v18, vcc, 1.0, v14, 1.0
	v_mul_f32_e32 v19, v18, v17
	v_fma_f32 v20, -v16, v19, v18
	v_fmac_f32_e32 v19, v20, v17
	v_fma_f32 v16, -v16, v19, v18
	v_div_fmas_f32 v16, v16, v17, v19
	v_div_fixup_f32 v14, v16, v14, 1.0
	v_pk_mul_f32 v[12:13], v[12:13], v[14:15] op_sel_hi:[1,0]
	v_mul_f32_e32 v16, v15, v14
	v_pk_mul_f32 v[36:37], v[12:13], v[36:37] op_sel:[1,0] op_sel_hi:[0,1]
	v_and_b32_e32 v39, 0xffff0000, v8
	v_pk_fma_f32 v[22:23], v[12:13], v[22:23], v[36:37]
	v_lshlrev_b32_e32 v36, 16, v5
	v_pk_fma_f32 v[22:23], v[16:17], v[38:39], v[22:23] op_sel_hi:[0,1,1]
	v_lshlrev_b32_e32 v38, 16, v1
	v_and_b32_e32 v39, 0xffff0000, v5
	v_and_b32_e32 v37, 0xffff0000, v1
	v_pk_mul_f32 v[38:39], v[12:13], v[38:39] op_sel:[1,0] op_sel_hi:[0,1]
	v_lshlrev_b32_e32 v40, 16, v9
	v_and_b32_e32 v41, 0xffff0000, v9
	v_pk_fma_f32 v[36:37], v[12:13], v[36:37], v[38:39]
	v_lshlrev_b32_e32 v18, 16, v3
	v_and_b32_e32 v19, 0xffff0000, v7
	v_pk_fma_f32 v[36:37], v[16:17], v[40:41], v[36:37] op_sel_hi:[0,1,1]
	v_lshlrev_b32_e32 v40, 16, v2
	v_and_b32_e32 v41, 0xffff0000, v6
	v_lshlrev_b32_e32 v14, 16, v7
	v_and_b32_e32 v15, 0xffff0000, v3
	v_lshlrev_b32_e32 v38, 16, v6
	v_and_b32_e32 v39, 0xffff0000, v2
	v_pk_mul_f32 v[40:41], v[12:13], v[40:41] op_sel:[1,0] op_sel_hi:[0,1]
	v_pk_mul_f32 v[18:19], v[12:13], v[18:19] op_sel:[1,0] op_sel_hi:[0,1]
	v_lshlrev_b32_e32 v20, 16, v11
	v_and_b32_e32 v21, 0xffff0000, v11
	v_lshlrev_b32_e32 v42, 16, v10
	v_and_b32_e32 v43, 0xffff0000, v10
	v_pk_fma_f32 v[38:39], v[12:13], v[38:39], v[40:41]
	v_pk_fma_f32 v[12:13], v[12:13], v[14:15], v[18:19]
	v_pk_fma_f32 v[38:39], v[16:17], v[42:43], v[38:39] op_sel_hi:[0,1,1]
	v_pk_fma_f32 v[16:17], v[16:17], v[20:21], v[12:13] op_sel_hi:[0,1,1]
	v_cvt_pk_bf16_f32 v12, v22, v23
	v_cvt_pk_bf16_f32 v13, v36, v37
	v_cvt_pk_bf16_f32 v14, v38, v39
	v_cvt_pk_bf16_f32 v15, v16, v17
	v_mad_i64_i32 v[16:17], s[8:9], s6, v213, v[30:31]
	global_store_dwordx4 v[16:17], v[12:15], off
	s_branch .LBB0_997
